# attention: masked hand-scheduled fast path for edge chunks (band validity masks once per chunk, unclamped bias index, p zeroed by mask)
# speedup vs baseline: 1.0037x; 1.0037x over previous
; #define LAS __attribute__((address_space(3)))
; __device__ __forceinline__ bf16x8 attn_scores(const f32x4 s0, const f32x4 s1, const LAS float* bt, int cs, bool interior, bool metal, int g, int qpos, int L, float& den) {
;     ...
;     } else {
; #pragma unroll
;         for (int e = 0; e < 8; ++e) {
;             const float sv = e < 4 ? s0[e & 3] : s1[e & 3];
;             const int relb = cs + e, pos = relb + qpos;
;             const int relm = 8 * g + e - qpos;
;             const bool bvalid = ((unsigned)(relb + 128) <= 256u) && ((unsigned)(pos - 16) < (unsigned)(L - 16));
;             const int rel = metal ? relm : relb;
;             const bool valid = metal || bvalid;
;             const int relc = rel < -128 ? -128 : (rel > 128 ? 128 : rel);
; __device__ __forceinline__ void attn_phase(LAS unsigned char* lds, const Args& a, int j, int bid, int G, int tid) {
;     ...
;                 for (int i = 0; i < 10; ++i) {
;                     const int chunk = i == 0 ? 0 : cb + i - 1;
;                     const int kb = lkoff + 32 * chunk * KSTR;
;                     const bf16x8 k00 = *(const LAS bf16x8*)(lds + kb), k01 = *(const LAS bf16x8*)(lds + kb + 64);
;                     const bf16x8 k10 = *(const LAS bf16x8*)(lds + kb + 4 * KSTR), k11 = *(const LAS bf16x8*)(lds + kb + 4 * KSTR + 64);
;                     const f32x4 z4 = (f32x4){0.f, 0.f, 0.f, 0.f};
;                     f32x4 s0[4], s1[4];
; #pragma unroll
;                     for (int h = 0; h < 4; ++h) { s0[h] = __builtin_amdgcn_mfma_f32_16x16x32_bf16(k00, qf0[h], z4, 0, 0, 0); s1[h] = __builtin_amdgcn_mfma_f32_16x16x32_bf16(k10, qf0[h], z4, 0, 0, 0); }
; #pragma unroll
;                     for (int h = 0; h < 4; ++h) { s0[h] = __builtin_amdgcn_mfma_f32_16x16x32_bf16(k01, qf1[h], s0[h], 0, 0, 0); s1[h] = __builtin_amdgcn_mfma_f32_16x16x32_bf16(k11, qf1[h], s1[h], 0, 0, 0); }
;                     const int cs = start - 16 - q0 + 32 * chunk + lb;
;                     const int pmin = start + 32 * chunk - 16;
;                     const bool interior = (chunk > 0) && (pmin >= q0 + 15 - 128) && (pmin + 31 <= q0 + 128) && (pmin >= 16) && (pmin + 31 < L);
;                     const bool metal = (chunk == 0) && (g < 2);
;                     bf16x8 pa[4];
; #pragma unroll
;                     for (int h = 0; h < 4; ++h) pa[h] = attn_scores(s0[h], s1[h], bt[h], cs, interior, metal, g, qpos, L, den[h]);
.LBB0_713:
	s_add_i32 s6, s46, s39
	s_cmp_lg_u32 s39, 0
	s_cselect_b32 s42, s6, 0
	s_mul_i32 s6, s42, 0x1200
	v_add_u32_e32 v16, s6, v173
	s_lshl_b32 s6, s42, 5
	s_add_i32 s24, s58, s6
	s_cmp_gt_i32 s42, 0
	v_add_u32_e32 v237, s6, v200
	s_cselect_b64 s[6:7], -1, 0
	s_cmp_ge_i32 s24, s28
	ds_read_b128 v[0:3], v16
	ds_read_b128 v[4:7], v16 offset:64
	ds_read_b128 v[12:15], v16 offset:576
	ds_read_b128 v[134:137], v16 offset:640
	v_lshl_add_u32 v214, s42, 6, v175
	ds_read_b128 v[148:151], v214 offset:59904
	v_add_u32_e32 v214, 0xea00, v214
	ds_read_b128 v[154:157], v214 offset:13568
	ds_read_b128 v[204:207], v214 offset:27136
	ds_read_b128 v[208:211], v214 offset:40704
	v_lshl_add_u32 v214, v237, 2, s63
	ds_read2_b32 v[238:239], v214 offset1:1
	ds_read2_b32 v[240:241], v214 offset0:2 offset1:3
	ds_read2_b32 v[242:243], v214 offset0:4 offset1:5
	ds_read2_b32 v[244:245], v214 offset0:6 offset1:7
	s_cselect_b64 s[18:19], -1, 0
	s_and_b64 s[6:7], s[6:7], s[18:19]
	s_cmp_le_i32 s24, s34
	s_cselect_b64 s[18:19], -1, 0
	s_cmp_gt_i32 s24, 31
	s_waitcnt lgkmcnt(11)
	v_mfma_f32_16x16x32_bf16 v[8:11], v[0:3], v[66:69], 0
	s_cselect_b64 s[22:23], -1, 0
	s_and_b64 s[18:19], s[18:19], s[22:23]
	s_or_b32 s22, s24, 15
	s_waitcnt lgkmcnt(9)
	v_mfma_f32_16x16x32_bf16 v[16:19], v[12:15], v[66:69], 0
	s_cmp_lt_i32 s22, s47
	s_cselect_b64 s[22:23], -1, 0
	s_and_b64 s[6:7], s[6:7], s[18:19]
	v_mfma_f32_16x16x32_bf16 v[24:27], v[12:15], v[78:81], 0
	s_and_b64 s[24:25], s[6:7], s[22:23]
	s_cmp_eq_u32 s42, 0
	s_cselect_b64 s[22:23], -1, 0
	v_mfma_f32_16x16x32_bf16 v[138:141], v[12:15], v[114:117], 0
	s_mov_b64 s[6:7], -1
	v_mfma_f32_16x16x32_bf16 v[142:145], v[12:15], v[122:125], 0
	v_mfma_f32_16x16x32_bf16 v[12:15], v[4:7], v[70:73], v[8:11]
	s_waitcnt lgkmcnt(8)
	v_mfma_f32_16x16x32_bf16 v[8:11], v[134:137], v[70:73], v[16:19]
	v_mfma_f32_16x16x32_bf16 v[20:23], v[0:3], v[78:81], 0
	v_mfma_f32_16x16x32_bf16 v[28:31], v[0:3], v[114:117], 0
	v_mfma_f32_16x16x32_bf16 v[0:3], v[0:3], v[122:125], 0
	v_mfma_f32_16x16x32_bf16 v[16:19], v[134:137], v[94:97], v[24:27]
	v_mfma_f32_16x16x32_bf16 v[24:27], v[134:137], v[118:121], v[138:141]
	v_mfma_f32_16x16x32_bf16 v[138:141], v[4:7], v[126:129], v[0:3]
	v_mfma_f32_16x16x32_bf16 v[20:23], v[4:7], v[94:97], v[20:23]
	v_mfma_f32_16x16x32_bf16 v[28:31], v[4:7], v[118:121], v[28:31]
	v_mfma_f32_16x16x32_bf16 v[134:137], v[134:137], v[126:129], v[142:145]
	s_and_b64 vcc, exec, s[24:25]
	s_cbranch_vccnz .Lattn_fast
	s_and_b64 vcc, exec, s[22:23]
	s_cbranch_vccz .Lattn_fastm
	s_waitcnt lgkmcnt(0)
	s_and_b64 vcc, s[22:23], s[4:5]
	v_add_u32_e32 v248, 0x80, v237
	v_cmp_gt_u32_e64 s[18:19], s78, v248
	v_add_u32_e32 v248, v237, v228
	v_cmp_gt_u32_e64 s[52:53], s35, v248
	s_and_b64 s[18:19], s[18:19], s[52:53]
	s_or_b64 s[18:19], vcc, s[18:19]
	v_cndmask_b32_e32 v247, v237, v229, vcc
	v_med3_i32 v238, v247, s55, v213
	v_add_u32_e32 v247, 1, v237
	v_add_u32_e32 v248, 0x81, v237
	v_cmp_gt_u32_e64 s[22:23], s78, v248
	v_add_u32_e32 v248, v247, v228
	v_cmp_gt_u32_e64 s[52:53], s35, v248
	s_and_b64 s[22:23], s[22:23], s[52:53]
	s_or_b64 s[22:23], vcc, s[22:23]
	v_cndmask_b32_e32 v247, v247, v230, vcc
	v_med3_i32 v239, v247, s55, v213
	v_add_u32_e32 v247, 2, v237
	v_add_u32_e32 v248, 0x82, v237
	v_cmp_gt_u32_e64 s[26:27], s78, v248
	v_add_u32_e32 v248, v247, v228
	v_cmp_gt_u32_e64 s[52:53], s35, v248
	s_and_b64 s[26:27], s[26:27], s[52:53]
	s_or_b64 s[26:27], vcc, s[26:27]
	v_cndmask_b32_e32 v247, v247, v231, vcc
	v_med3_i32 v240, v247, s55, v213
	v_add_u32_e32 v247, 3, v237
	v_add_u32_e32 v248, 0x83, v237
	v_cmp_gt_u32_e64 s[30:31], s78, v248
	v_add_u32_e32 v248, v247, v228
	v_cmp_gt_u32_e64 s[52:53], s35, v248
	s_and_b64 s[30:31], s[30:31], s[52:53]
	s_or_b64 s[30:31], vcc, s[30:31]
	v_cndmask_b32_e32 v247, v247, v232, vcc
	v_med3_i32 v241, v247, s55, v213
	v_add_u32_e32 v247, 4, v237
	v_add_u32_e32 v248, 0x84, v237
	v_cmp_gt_u32_e64 s[36:37], s78, v248
	v_add_u32_e32 v248, v247, v228
	v_cmp_gt_u32_e64 s[52:53], s35, v248
	s_and_b64 s[36:37], s[36:37], s[52:53]
	s_or_b64 s[36:37], vcc, s[36:37]
	v_cndmask_b32_e32 v247, v247, v233, vcc
	v_med3_i32 v242, v247, s55, v213
	v_add_u32_e32 v247, 5, v237
	v_add_u32_e32 v248, 0x85, v237
	v_cmp_gt_u32_e64 s[40:41], s78, v248
	v_add_u32_e32 v248, v247, v228
	v_cmp_gt_u32_e64 s[52:53], s35, v248
	s_and_b64 s[40:41], s[40:41], s[52:53]
	s_or_b64 s[40:41], vcc, s[40:41]
	v_cndmask_b32_e32 v247, v247, v234, vcc
	v_med3_i32 v243, v247, s55, v213
	v_add_u32_e32 v247, 6, v237
	v_add_u32_e32 v248, 0x86, v237
	v_cmp_gt_u32_e64 s[44:45], s78, v248
	v_add_u32_e32 v248, v247, v228
	v_cmp_gt_u32_e64 s[52:53], s35, v248
	s_and_b64 s[44:45], s[44:45], s[52:53]
	s_or_b64 s[44:45], vcc, s[44:45]
	v_cndmask_b32_e32 v247, v247, v235, vcc
	v_med3_i32 v244, v247, s55, v213
	v_add_u32_e32 v247, 7, v237
	v_add_u32_e32 v248, 0x87, v237
	v_cmp_gt_u32_e64 s[48:49], s78, v248
	v_add_u32_e32 v248, v247, v228
	v_cmp_gt_u32_e64 s[52:53], s35, v248
	s_and_b64 s[48:49], s[48:49], s[52:53]
	s_or_b64 s[48:49], vcc, s[48:49]
	v_cndmask_b32_e32 v247, v247, v236, vcc
	v_med3_i32 v245, v247, s55, v213
	v_lshl_add_u32 v0, v238, 2, s62
	v_lshl_add_u32 v1, v239, 2, s62
	v_lshl_add_u32 v2, v240, 2, s62
	v_lshl_add_u32 v3, v241, 2, s62
	v_lshl_add_u32 v4, v242, 2, s62
	v_lshl_add_u32 v5, v243, 2, s62
	v_lshl_add_u32 v6, v244, 2, s62
	v_lshl_add_u32 v7, v245, 2, s62
	ds_read_b32 v0, v0 offset:512
	ds_read_b32 v1, v1 offset:512
	ds_read_b32 v2, v2 offset:512
	ds_read_b32 v3, v3 offset:512
	ds_read_b32 v4, v4 offset:512
	ds_read_b32 v5, v5 offset:512
	ds_read_b32 v6, v6 offset:512
	ds_read_b32 v7, v7 offset:512
	s_waitcnt lgkmcnt(7)
	v_add_f32_e32 v0, v12, v0
	v_exp_f32_e32 v0, v0
	s_waitcnt lgkmcnt(6)
	v_add_f32_e32 v1, v13, v1
	v_exp_f32_e32 v1, v1
	s_waitcnt lgkmcnt(5)
	v_add_f32_e32 v2, v14, v2
	v_exp_f32_e32 v2, v2
	s_waitcnt lgkmcnt(4)
	v_add_f32_e32 v3, v15, v3
	v_exp_f32_e32 v3, v3
	s_waitcnt lgkmcnt(3)
	v_add_f32_e32 v4, v8, v4
	v_cndmask_b32_e64 v0, 0, v0, s[18:19]
	v_exp_f32_e32 v4, v4
	s_waitcnt lgkmcnt(2)
	v_add_f32_e32 v5, v9, v5
	v_add_f32_e32 v142, v130, v0
	v_cndmask_b32_e64 v1, 0, v1, s[22:23]
	v_exp_f32_e32 v5, v5
	s_waitcnt lgkmcnt(1)
	v_add_f32_e32 v6, v10, v6
	v_add_f32_e32 v142, v142, v1
	v_cndmask_b32_e64 v2, 0, v2, s[26:27]
	v_exp_f32_e32 v6, v6
	s_waitcnt lgkmcnt(0)
	v_add_f32_e32 v7, v11, v7
	v_add_f32_e32 v142, v142, v2
	v_cndmask_b32_e64 v3, 0, v3, s[30:31]
	v_exp_f32_e32 v7, v7
	v_add_f32_e32 v142, v142, v3
	v_cndmask_b32_e64 v4, 0, v4, s[36:37]
	v_add_f32_e32 v142, v142, v4
	v_cndmask_b32_e64 v5, 0, v5, s[40:41]
	v_add_f32_e32 v142, v142, v5
	v_cndmask_b32_e64 v6, 0, v6, s[44:45]
	v_add_f32_e32 v146, v142, v6
	v_mov_b64_e32 v[144:145], v[132:133]
	v_cndmask_b32_e64 v7, 0, v7, s[48:49]
	v_mov_b64_e32 v[142:143], v[130:131]
	v_add_f32_e32 v246, v146, v7
	s_mov_b64 s[6:7], 0

; #define LAS __attribute__((address_space(3)))
; __device__ __forceinline__ unsigned cvtpk(float lo, float hi) { f32x2 v = {lo, hi}; bf16x2_t b = __builtin_convertvector(v, bf16x2_t); return __builtin_bit_cast(unsigned, b); }
; __device__ __forceinline__ bf16x8 attn_scores(const f32x4 s0, const f32x4 s1, const LAS float* bt, int cs, bool interior, bool metal, int g, int qpos, int L, float& den) {
;     float p[8];
;     if (interior) {
; #pragma unroll
;         for (int e = 0; e < 8; ++e) { const float sv = e < 4 ? s0[e & 3] : s1[e & 3]; p[e] = __builtin_amdgcn_exp2f(sv + bt[cs + e]); den += p[e]; }
;     } else {
; #pragma unroll
;         for (int e = 0; e < 8; ++e) {
;             const float sv = e < 4 ? s0[e & 3] : s1[e & 3];
;             const int relb = cs + e, pos = relb + qpos;
;             const int relm = 8 * g + e - qpos;
;             const bool bvalid = ((unsigned)(relb + 128) <= 256u) && ((unsigned)(pos - 16) < (unsigned)(L - 16));
;             const int rel = metal ? relm : relb;
;             const bool valid = metal || bvalid;
;             const int relc = rel < -128 ? -128 : (rel > 128 ? 128 : rel);
;             const float val = __builtin_amdgcn_exp2f(sv + bt[relc]);
;             p[e] = valid ? val : 0.f;
;             den += p[e];
;         }
;     }
;     u32x4 pp; pp.x = cvtpk(p[0], p[1]); pp.y = cvtpk(p[2], p[3]); pp.z = cvtpk(p[4], p[5]); pp.w = cvtpk(p[6], p[7]);
;     return __builtin_bit_cast(bf16x8, pp);
; __device__ __forceinline__ void attn_phase(LAS unsigned char* lds, const Args& a, int j, int bid, int G, int tid) {
;     ...
;                     const int vbo = lvoff + 64 * chunk;
; #pragma unroll
;                     for (int dt = 0; dt < 4; ++dt) {
;                         const bf16x8 vb = *(const LAS bf16x8*)(lds + vbo + dt * 16 * VSTR);
; #pragma unroll
;                         for (int h = 0; h < 4; ++h) oh[h][dt] = __builtin_amdgcn_mfma_f32_16x16x32_bf16(pa[h], vb, oh[h][dt], 0, 0, 0);
;                     }
.Lattn_fastm:
	v_lshl_add_u32 v214, v237, 2, s67
	ds_read2_b32 v[248:249], v214 offset1:1
	ds_read2_b32 v[250:251], v214 offset0:2 offset1:3
	ds_read2_b32 v[252:253], v214 offset0:4 offset1:5
	ds_read2_b32 v[146:147], v214 offset0:6 offset1:7
	v_add_u32_e32 v247, 0x80, v237
	v_cmp_gt_u32_e64 s[18:19], s78, v247
	v_add3_u32 v247, v237, v228, 0
	v_cmp_gt_u32_e64 s[52:53], s35, v247
	s_and_b64 s[18:19], s[18:19], s[52:53]
	v_add_u32_e32 v247, 0x81, v237
	v_cmp_gt_u32_e64 s[22:23], s78, v247
	v_add3_u32 v247, v237, v228, 1
	v_cmp_gt_u32_e64 s[52:53], s35, v247
	s_and_b64 s[22:23], s[22:23], s[52:53]
	v_add_u32_e32 v247, 0x82, v237
	v_cmp_gt_u32_e64 s[26:27], s78, v247
	v_add3_u32 v247, v237, v228, 2
	v_cmp_gt_u32_e64 s[52:53], s35, v247
	s_and_b64 s[26:27], s[26:27], s[52:53]
	v_add_u32_e32 v247, 0x83, v237
	v_cmp_gt_u32_e64 s[30:31], s78, v247
	v_add3_u32 v247, v237, v228, 3
	v_cmp_gt_u32_e64 s[52:53], s35, v247
	s_and_b64 s[30:31], s[30:31], s[52:53]
	v_add_u32_e32 v247, 0x84, v237
	v_cmp_gt_u32_e64 s[36:37], s78, v247
	v_add3_u32 v247, v237, v228, 4
	v_cmp_gt_u32_e64 s[52:53], s35, v247
	s_and_b64 s[36:37], s[36:37], s[52:53]
	v_add_u32_e32 v247, 0x85, v237
	v_cmp_gt_u32_e64 s[40:41], s78, v247
	v_add3_u32 v247, v237, v228, 5
	v_cmp_gt_u32_e64 s[52:53], s35, v247
	s_and_b64 s[40:41], s[40:41], s[52:53]
	v_add_u32_e32 v247, 0x86, v237
	v_cmp_gt_u32_e64 s[44:45], s78, v247
	v_add3_u32 v247, v237, v228, 6
	v_cmp_gt_u32_e64 s[52:53], s35, v247
	s_and_b64 s[44:45], s[44:45], s[52:53]
	v_add_u32_e32 v247, 0x87, v237
	v_cmp_gt_u32_e64 s[48:49], s78, v247
	v_add3_u32 v247, v237, v228, 7
	v_cmp_gt_u32_e64 s[52:53], s35, v247
	s_and_b64 s[48:49], s[48:49], s[52:53]
	s_waitcnt lgkmcnt(4)
	v_pk_add_f32 v[0:1], v[12:13], v[238:239]
	v_pk_add_f32 v[2:3], v[14:15], v[240:241]
	v_pk_add_f32 v[4:5], v[8:9], v[242:243]
	v_pk_add_f32 v[6:7], v[10:11], v[244:245]
	v_lshl_add_u32 v214, v237, 2, s73
	ds_read2_b32 v[238:239], v214 offset1:1
	ds_read2_b32 v[240:241], v214 offset0:2 offset1:3
	ds_read2_b32 v[242:243], v214 offset0:4 offset1:5
	ds_read2_b32 v[244:245], v214 offset0:6 offset1:7
	v_exp_f32_e32 v0, v0
	v_exp_f32_e32 v1, v1
	v_exp_f32_e32 v2, v2
	v_exp_f32_e32 v3, v3
	v_exp_f32_e32 v4, v4
	v_exp_f32_e32 v5, v5
	v_exp_f32_e32 v6, v6
	v_exp_f32_e32 v7, v7
	v_cndmask_b32_e64 v0, 0, v0, s[18:19]
	v_cndmask_b32_e64 v1, 0, v1, s[22:23]
	v_cndmask_b32_e64 v2, 0, v2, s[26:27]
	v_cndmask_b32_e64 v3, 0, v3, s[30:31]
	v_cndmask_b32_e64 v4, 0, v4, s[36:37]
	v_cndmask_b32_e64 v5, 0, v5, s[40:41]
	v_cndmask_b32_e64 v6, 0, v6, s[44:45]
	v_cndmask_b32_e64 v7, 0, v7, s[48:49]
	v_pk_add_f32 v[8:9], v[0:1], v[2:3]
	v_pk_add_f32 v[10:11], v[4:5], v[6:7]
	v_pk_add_f32 v[8:9], v[8:9], v[10:11]
	v_add_f32_e32 v8, v8, v9
	v_add_f32_e32 v130, v130, v8
	v_cvt_pk_bf16_f32 v0, v0, v1
	v_cvt_pk_bf16_f32 v1, v2, v3
	v_cvt_pk_bf16_f32 v2, v4, v5
	v_cvt_pk_bf16_f32 v3, v6, v7
	s_waitcnt lgkmcnt(4)
	v_pk_add_f32 v[8:9], v[20:21], v[248:249]
	v_pk_add_f32 v[10:11], v[22:23], v[250:251]
	v_pk_add_f32 v[12:13], v[16:17], v[252:253]
	v_pk_add_f32 v[14:15], v[18:19], v[146:147]
	v_mfma_f32_16x16x32_bf16 v[110:113], v[0:3], v[148:151], v[110:113]
	v_lshl_add_u32 v214, v237, 2, s75
	ds_read2_b32 v[248:249], v214 offset1:1
	ds_read2_b32 v[250:251], v214 offset0:2 offset1:3
	ds_read2_b32 v[252:253], v214 offset0:4 offset1:5
	ds_read2_b32 v[146:147], v214 offset0:6 offset1:7
	v_exp_f32_e32 v8, v8
	v_exp_f32_e32 v9, v9
	v_mfma_f32_16x16x32_bf16 v[106:109], v[0:3], v[154:157], v[106:109]
	v_exp_f32_e32 v10, v10
	v_exp_f32_e32 v11, v11
	v_mfma_f32_16x16x32_bf16 v[102:105], v[0:3], v[204:207], v[102:105]
	v_exp_f32_e32 v12, v12
	v_exp_f32_e32 v13, v13
	v_mfma_f32_16x16x32_bf16 v[98:101], v[0:3], v[208:211], v[98:101]
	v_exp_f32_e32 v14, v14
	v_exp_f32_e32 v15, v15
	v_cndmask_b32_e64 v8, 0, v8, s[18:19]
	v_cndmask_b32_e64 v9, 0, v9, s[22:23]
	v_cndmask_b32_e64 v10, 0, v10, s[26:27]
	v_cndmask_b32_e64 v11, 0, v11, s[30:31]
	v_cndmask_b32_e64 v12, 0, v12, s[36:37]
	v_cndmask_b32_e64 v13, 0, v13, s[40:41]
	v_cndmask_b32_e64 v14, 0, v14, s[44:45]
	v_cndmask_b32_e64 v15, 0, v15, s[48:49]
	v_pk_add_f32 v[20:21], v[8:9], v[10:11]
	v_pk_add_f32 v[22:23], v[12:13], v[14:15]
	v_pk_add_f32 v[20:21], v[20:21], v[22:23]
	v_add_f32_e32 v20, v20, v21
	v_add_f32_e32 v131, v131, v20
	v_cvt_pk_bf16_f32 v8, v8, v9
	v_cvt_pk_bf16_f32 v9, v10, v11
	v_cvt_pk_bf16_f32 v10, v12, v13
	v_cvt_pk_bf16_f32 v11, v14, v15
	s_waitcnt lgkmcnt(4)
; #define LAS __attribute__((address_space(3)))
; __device__ __forceinline__ unsigned cvtpk(float lo, float hi) { f32x2 v = {lo, hi}; bf16x2_t b = __builtin_convertvector(v, bf16x2_t); return __builtin_bit_cast(unsigned, b); }
; __device__ __forceinline__ bf16x8 attn_scores(const f32x4 s0, const f32x4 s1, const LAS float* bt, int cs, bool interior, bool metal, int g, int qpos, int L, float& den) {
;     ...
;     if (interior) {
; #pragma unroll
;         for (int e = 0; e < 8; ++e) { const float sv = e < 4 ? s0[e & 3] : s1[e & 3]; p[e] = __builtin_amdgcn_exp2f(sv + bt[cs + e]); den += p[e]; }
;     } else {
; #pragma unroll
;         for (int e = 0; e < 8; ++e) {
;             const float sv = e < 4 ? s0[e & 3] : s1[e & 3];
;             const int relb = cs + e, pos = relb + qpos;
;             const int relm = 8 * g + e - qpos;
;             const bool bvalid = ((unsigned)(relb + 128) <= 256u) && ((unsigned)(pos - 16) < (unsigned)(L - 16));
;             const int rel = metal ? relm : relb;
;             const bool valid = metal || bvalid;
;             const int relc = rel < -128 ? -128 : (rel > 128 ? 128 : rel);
;             const float val = __builtin_amdgcn_exp2f(sv + bt[relc]);
;             p[e] = valid ? val : 0.f;
;             den += p[e];
;         }
;     }
;     u32x4 pp; pp.x = cvtpk(p[0], p[1]); pp.y = cvtpk(p[2], p[3]); pp.z = cvtpk(p[4], p[5]); pp.w = cvtpk(p[6], p[7]);
;     return __builtin_bit_cast(bf16x8, pp);
; __device__ __forceinline__ void attn_phase(LAS unsigned char* lds, const Args& a, int j, int bid, int G, int tid) {
;     ...
;                     const int vbo = lvoff + 64 * chunk;
; #pragma unroll
;                     for (int dt = 0; dt < 4; ++dt) {
;                         const bf16x8 vb = *(const LAS bf16x8*)(lds + vbo + dt * 16 * VSTR);
; #pragma unroll
;                         for (int h = 0; h < 4; ++h) oh[h][dt] = __builtin_amdgcn_mfma_f32_16x16x32_bf16(pa[h], vb, oh[h][dt], 0, 0, 0);
;                     }
	v_pk_add_f32 v[16:17], v[28:29], v[238:239]
	v_pk_add_f32 v[18:19], v[30:31], v[240:241]
	v_pk_add_f32 v[20:21], v[24:25], v[242:243]
	v_pk_add_f32 v[22:23], v[26:27], v[244:245]
	v_mfma_f32_16x16x32_bf16 v[90:93], v[8:11], v[148:151], v[90:93]
	v_exp_f32_e32 v16, v16
	v_exp_f32_e32 v17, v17
	v_mfma_f32_16x16x32_bf16 v[86:89], v[8:11], v[154:157], v[86:89]
	v_exp_f32_e32 v18, v18
	v_exp_f32_e32 v19, v19
	v_mfma_f32_16x16x32_bf16 v[82:85], v[8:11], v[204:207], v[82:85]
	v_exp_f32_e32 v20, v20
	v_exp_f32_e32 v21, v21
	v_mfma_f32_16x16x32_bf16 v[74:77], v[8:11], v[208:211], v[74:77]
	v_exp_f32_e32 v22, v22
	v_exp_f32_e32 v23, v23
	v_cndmask_b32_e64 v16, 0, v16, s[18:19]
	v_cndmask_b32_e64 v17, 0, v17, s[22:23]
	v_cndmask_b32_e64 v18, 0, v18, s[26:27]
	v_cndmask_b32_e64 v19, 0, v19, s[30:31]
	v_cndmask_b32_e64 v20, 0, v20, s[36:37]
	v_cndmask_b32_e64 v21, 0, v21, s[40:41]
	v_cndmask_b32_e64 v22, 0, v22, s[44:45]
	v_cndmask_b32_e64 v23, 0, v23, s[48:49]
	v_pk_add_f32 v[24:25], v[16:17], v[18:19]
	v_pk_add_f32 v[26:27], v[20:21], v[22:23]
	v_pk_add_f32 v[24:25], v[24:25], v[26:27]
	v_add_f32_e32 v24, v24, v25
	v_add_f32_e32 v132, v132, v24
	v_cvt_pk_bf16_f32 v16, v16, v17
	v_cvt_pk_bf16_f32 v17, v18, v19
	v_cvt_pk_bf16_f32 v18, v20, v21
	v_cvt_pk_bf16_f32 v19, v22, v23
	s_waitcnt lgkmcnt(0)
	v_pk_add_f32 v[24:25], v[138:139], v[248:249]
	v_pk_add_f32 v[26:27], v[140:141], v[250:251]
	v_pk_add_f32 v[28:29], v[134:135], v[252:253]
	v_pk_add_f32 v[30:31], v[136:137], v[146:147]
	v_mfma_f32_16x16x32_bf16 v[62:65], v[16:19], v[148:151], v[62:65]
	v_exp_f32_e32 v24, v24
	v_exp_f32_e32 v25, v25
	v_mfma_f32_16x16x32_bf16 v[58:61], v[16:19], v[154:157], v[58:61]
	v_exp_f32_e32 v26, v26
	v_exp_f32_e32 v27, v27
	v_mfma_f32_16x16x32_bf16 v[54:57], v[16:19], v[204:207], v[54:57]
	v_exp_f32_e32 v28, v28
	v_exp_f32_e32 v29, v29
	v_mfma_f32_16x16x32_bf16 v[50:53], v[16:19], v[208:211], v[50:53]
	v_exp_f32_e32 v30, v30
	v_exp_f32_e32 v31, v31
	v_cndmask_b32_e64 v24, 0, v24, s[18:19]
	v_cndmask_b32_e64 v25, 0, v25, s[22:23]
	v_cndmask_b32_e64 v26, 0, v26, s[26:27]
	v_cndmask_b32_e64 v27, 0, v27, s[30:31]
	v_cndmask_b32_e64 v28, 0, v28, s[36:37]
	v_cndmask_b32_e64 v29, 0, v29, s[40:41]
	v_cndmask_b32_e64 v30, 0, v30, s[44:45]
	v_cndmask_b32_e64 v31, 0, v31, s[48:49]
	v_pk_add_f32 v[138:139], v[24:25], v[26:27]
	v_pk_add_f32 v[140:141], v[28:29], v[30:31]
	v_pk_add_f32 v[138:139], v[138:139], v[140:141]
	v_add_f32_e32 v138, v138, v139
	v_add_f32_e32 v133, v133, v138
	v_cvt_pk_bf16_f32 v4, v24, v25
	v_cvt_pk_bf16_f32 v5, v26, v27
	v_cvt_pk_bf16_f32 v6, v28, v29
	v_cvt_pk_bf16_f32 v7, v30, v31
	s_add_i32 s39, s39, 1
	s_cmp_eq_u32 s39, 10
	v_mfma_f32_16x16x32_bf16 v[46:49], v[4:7], v[148:151], v[46:49]
	v_mfma_f32_16x16x32_bf16 v[42:45], v[4:7], v[154:157], v[42:45]
	v_mfma_f32_16x16x32_bf16 v[38:41], v[4:7], v[204:207], v[38:41]
	v_mfma_f32_16x16x32_bf16 v[34:37], v[4:7], v[208:211], v[34:37]
	s_cbranch_scc1 .LBB0_655
	s_branch .LBB0_713
